# dilated unit prologue: Q/tile-0,1 wait + barrier moved behind the loop set-up and the DMA of tiles 2,3 (they start one latency earlier; vmcnt(8))
# baseline (speedup 1.0000x reference)
; #define DUPREP(k) for (int rep_ = 0; rep_ < 1 + ((MK_DUP >> (k)) & 1); ++rep_)
; __device__ __forceinline__ int otid() { int t = threadIdx.x; asm volatile("" : "+v"(t)); return t; }
; __device__ __forceinline__ int v_rd_base(int lane) { return ((lane & 3) << 3) | (((lane >> 2) & 3) << 6) | (((lane >> 4) & 1) << 5) | (((lane >> 5) & 1) << 8); }
;     ...
;   const int tid = otid(), wid = __builtin_amdgcn_readfirstlane(tid >> 6), lane = tid & 63, r32 = lane & 31, hi = lane >> 5;
;   char* V_lds = lds + 4 * SHM_K; char* K_lds = lds;
;   float* ws = (float*)(lds + 4 * SHM_K + 4 * SHM_V) + wid * 64; float* li_l = ws; float* al_l = ws + 32;
;   float m_reg = -1e30f, l_reg = 0; f32x16 o[4] = {}; bf16x8 qr[8];
;   const bf16* Qw = Qb + (long)(wid * QBLK + r32) * qs + hi * 8;
; #pragma unroll
;   for (int d0 = 0; d0 < 8; ++d0) qr[d0] = St::ld8(Qw + d0 * 16);
;   const int vb0 = (int)(uintptr_t)V_lds + v_rd_base(lane);
;   const int kb = DIL ? i0 - 64 : 0;
;     ...
;   int krow[2], kcol[2], vrow[2], vcol[2];
; #pragma unroll
;   for (int i = 0; i < 2; ++i) { const int pc = 2 * wid + i;
;     krow[i] = pc * 4 + (lane >> 4); kcol[i] = (((lane & 15) ^ (krow[i] & 7)) << 3);
;     const int sub = pc * 2 + (lane >> 5), kk = ((sub >> 2) << 3) + ((lane & 31) >> 2);
;     vrow[i] = kk; vcol[i] = ((sub & 3) << 5) + ((lane & 3) << 3); }
;   unsigned kdo[2], vdo[2];
; #pragma unroll
;   for (int i = 0; i < 2; ++i) { kdo[i] = (unsigned)(krow[i] * (int)ks + kcol[i]); vdo[i] = (unsigned)(vrow[i] * (int)ks + vcol[i]); }
; __global__ void __launch_bounds__(512, 2) mk_fwd(Params p) {
;     ...
;                 DUPREP(3) for (int u = vcu; u < 1536; u += G) {
;                     const int pt = u >> 9, rem = u & 511, b = rem >> 8, h = (rem >> 5) & 7, w = rem & 31;
;                     const int d = (pt == 0) ? 1 : (pt == 1) ? 4 : 16, res = w & (d - 1), blk = w / d, i0 = blk * 256, nsub = T / d;
;                     const float slope = __builtin_amdgcn_exp2f(-(float)(h + 1));
;                     const float nslopeC = -slope * (float)d * att::LOG2E;
;                     const size_t tok0 = (size_t)b * T + res;
;                     const att::bf16* Pb = (const att::bf16*)PROJ + ((size_t)h * M + tok0) * HD;
;                     const long rs = (long)d * HD;
.LBB0_137:
	s_cmpk_gt_i32 s99, 0x5ff
	s_cbranch_scc1 .LBB0_157
	s_ashr_i32 s36, s99, 9
	s_bfe_u32 s9, s99, 0x30005
	s_and_b32 s8, s99, 31
	s_cmp_eq_u32 s36, 1
	s_cselect_b64 s[2:3], -1, 0
	s_and_b64 s[0:1], s[2:3], exec
	s_cselect_b32 s10, 4, 16
	s_cselect_b32 s11, 2, 4
	s_cselect_b32 s12, 9, 11
	s_cmpk_lt_u32 s99, 0x200
	s_cselect_b64 s[18:19], -1, 0
	s_and_b64 s[0:1], s[18:19], exec
	s_cselect_b32 s15, 1, s10
	s_cselect_b32 s0, 0, s11
	s_cselect_b32 s10, 7, s12
	s_add_i32 s1, s15, -1
	s_and_b32 s1, s1, s8
	s_lshr_b32 s8, s8, s0
	s_lshr_b32 s11, 0x2000, s0
	s_lshl_b32 s0, s99, 5
	s_and_b32 s0, s0, 0x2000
	s_lshl_b32 s40, s8, 8
	s_add_i32 s21, s9, 1
	s_or_b32 s52, s1, s0
	s_lshl_b32 s0, s9, 22
	s_add_u32 s0, s34, s0
	s_addc_u32 s1, s35, 0
	s_lshl_b32 s8, s52, 8
	s_mov_b32 s41, s53
	s_add_u32 s8, s0, s8
	s_addc_u32 s14, s1, 0
	s_lshl_b64 s[0:1], s[40:41], s10
	s_lshl_b64 s[0:1], s[0:1], 1
	s_add_u32 s12, s8, s0
	s_addc_u32 s13, s14, s1
	s_add_u32 s42, s8, 0x7000000
	s_addc_u32 s43, s14, 0
	v_mov_b32_e32 v10, v214
	s_add_u32 s0, s8, 0x9000000
	s_addc_u32 s1, s14, 0
	v_readfirstlane_b32 s23, v10
	s_ashr_i32 s8, s23, 6
	v_and_b32_e32 v141, 31, v10
	s_lshl_b32 s22, s8, 5
	v_or_b32_e32 v132, s22, v141
	v_ashrrev_i32_e32 v133, 31, v132
	v_bfe_u32 v142, v10, 5, 1
	v_lshlrev_b64 v[2:3], s10, v[132:133]
	v_lshl_add_u64 v[2:3], v[2:3], 1, s[12:13]
	v_lshlrev_b32_e32 v130, 4, v142
	v_mov_b32_e32 v131, v1
	v_lshl_add_u64 v[2:3], v[2:3], 0, v[130:131]
	s_mov_b64 s[12:13], 0x5000000
	v_lshl_add_u64 v[4:5], v[2:3], 0, s[12:13]
	s_mov_b32 s12, 0x5000000
	s_lshl_b32 s37, s8, 3
	v_bfe_u32 v131, v10, 4, 2
	v_add_co_u32_e32 v2, vcc, s12, v2
	v_lshlrev_b32_e32 v13, 3, v10
	v_or_b32_e32 v14, s37, v131
	v_and_b32_e32 v0, 32, v10
	s_sub_i32 s25, s40, 64
	v_addc_co_u32_e32 v3, vcc, 0, v3, vcc
	global_load_dwordx4 v[98:101], v[4:5], off offset:32
	global_load_dwordx4 v[102:105], v[4:5], off offset:64
	global_load_dwordx4 v[106:109], v[4:5], off offset:96
	global_load_dwordx4 v[110:113], v[4:5], off offset:128
	global_load_dwordx4 v[114:117], v[4:5], off offset:160
	global_load_dwordx4 v[118:121], v[4:5], off offset:192
	global_load_dwordx4 v[122:125], v[2:3], off
	global_load_dwordx4 v[126:129], v[4:5], off offset:224
	v_and_or_b32 v5, v13, 24, v0
	v_add_u32_e32 v0, s25, v14
	s_add_i32 s12, s11, -1
	v_max_i32_e32 v0, 0, v0
	v_min_u32_e32 v0, s12, v0
	v_bitop3_b32 v4, v131, v10, 15 bitop3:0x78
	s_lshl_b32 s38, s8, 11
	v_lshlrev_b64 v[2:3], s10, v[0:1]
	v_bfe_u32 v11, v10, 2, 3
	v_lshl_add_u64 v[2:3], v[2:3], 1, s[42:43]
	v_lshlrev_b32_e32 v0, 4, v4
	s_add_i32 s13, s38, 0
	v_or_b32_e32 v12, s37, v11
	v_lshl_add_u64 v[2:3], v[2:3], 0, v[0:1]
	s_mov_b32 m0, s13
	v_or_b32_e32 v15, 4, v14
	global_load_lds_dwordx4 v[2:3], off
	v_add_u32_e32 v2, s25, v12
	v_max_i32_e32 v2, 0, v2
	v_add_u32_e32 v6, s25, v15
	v_min_u32_e32 v2, s12, v2
	v_mov_b32_e32 v3, v1
	v_max_i32_e32 v6, 0, v6
	v_and_b32_e32 v140, 15, v10
	v_lshlrev_b64 v[2:3], s10, v[2:3]
	v_min_u32_e32 v6, s12, v6
	v_mov_b32_e32 v7, v1
	v_bitop3_b32 v8, v15, v140, 7 bitop3:0x6c
	v_lshl_add_u64 v[2:3], v[2:3], 1, s[0:1]
	v_lshlrev_b32_e32 v4, 1, v5
	v_mov_b32_e32 v5, v1
	s_add_i32 s14, s88, s38
	v_lshlrev_b64 v[6:7], s10, v[6:7]
	v_lshl_add_u64 v[2:3], v[2:3], 0, v[4:5]
	s_mov_b32 m0, s14
	v_lshl_add_u64 v[6:7], v[6:7], 1, s[42:43]
	v_lshlrev_b32_e32 v8, 4, v8
	v_mov_b32_e32 v9, v1
	global_load_lds_dwordx4 v[2:3], off
	v_lshl_add_u64 v[6:7], v[6:7], 0, v[8:9]
	s_or_b32 s25, s38, 0x400
	s_add_i32 m0, s13, 0x400
	v_lshl_add_u64 v[2:3], v[2:3], 0, s[70:71]
	global_load_lds_dwordx4 v[6:7], off
	s_add_i32 m0, s88, s25
	v_add_u32_e32 v6, s40, v15
	global_load_lds_dwordx4 v[2:3], off
	v_add_u32_e32 v2, s40, v14
	v_max_i32_e32 v2, 0, v2
	v_min_u32_e32 v2, s12, v2
	v_mov_b32_e32 v3, v1
	v_lshlrev_b64 v[2:3], s10, v[2:3]
	v_lshl_add_u64 v[2:3], v[2:3], 1, s[42:43]
	v_lshl_add_u64 v[2:3], v[2:3], 0, v[0:1]
	s_add_i32 m0, s13, 0x4000
	v_max_i32_e32 v6, 0, v6
	global_load_lds_dwordx4 v[2:3], off
	v_add_u32_e32 v2, s40, v12
	v_max_i32_e32 v2, 0, v2
	v_min_u32_e32 v2, s12, v2
	v_mov_b32_e32 v3, v1
	v_lshlrev_b64 v[2:3], s10, v[2:3]
	v_min_u32_e32 v6, s12, v6
	v_mov_b32_e32 v7, v1
	v_lshl_add_u64 v[2:3], v[2:3], 1, s[0:1]
	v_lshlrev_b64 v[6:7], s10, v[6:7]
	v_lshl_add_u64 v[2:3], v[2:3], 0, v[4:5]
	s_add_i32 m0, s89, s38
	v_lshl_add_u64 v[6:7], v[6:7], 1, s[42:43]
	global_load_lds_dwordx4 v[2:3], off
	v_lshl_add_u64 v[6:7], v[6:7], 0, v[8:9]
	s_add_i32 m0, s13, 0x4400
	v_lshl_add_u64 v[2:3], v[2:3], 0, s[70:71]
	global_load_lds_dwordx4 v[6:7], off
	s_add_i32 m0, s89, s25
	v_lshlrev_b32_e32 v6, 4, v10
	global_load_lds_dwordx4 v[2:3], off
	v_cvt_f32_ubyte0_e32 v2, s21
	v_exp_f32_e64 v2, -v2
	v_cvt_f32_ubyte0_e32 v3, s15
; __device__ __forceinline__ int v_rd_base(int lane) { return ((lane & 3) << 3) | (((lane >> 2) & 3) << 6) | (((lane >> 4) & 1) << 5) | (((lane >> 5) & 1) << 8); }
;     ...
;   float m_reg = -1e30f, l_reg = 0; f32x16 o[4] = {}; bf16x8 qr[8];
;   const bf16* Qw = Qb + (long)(wid * QBLK + r32) * qs + hi * 8;
; #pragma unroll
;   for (int d0 = 0; d0 < 8; ++d0) qr[d0] = St::ld8(Qw + d0 * 16);
;   const int vb0 = (int)(uintptr_t)V_lds + v_rd_base(lane);
;   const int kb = DIL ? i0 - 64 : 0;
;     ...
;   int krow[2], kcol[2], vrow[2], vcol[2];
; #pragma unroll
;   for (int i = 0; i < 2; ++i) { const int pc = 2 * wid + i;
;     krow[i] = pc * 4 + (lane >> 4); kcol[i] = (((lane & 15) ^ (krow[i] & 7)) << 3);
;     const int sub = pc * 2 + (lane >> 5), kk = ((sub >> 2) << 3) + ((lane & 31) >> 2);
;     vrow[i] = kk; vcol[i] = ((sub & 3) << 5) + ((lane & 3) << 3); }
;   unsigned kdo[2], vdo[2];
; #pragma unroll
;   for (int i = 0; i < 2; ++i) { kdo[i] = (unsigned)(krow[i] * (int)ks + kcol[i]); vdo[i] = (unsigned)(vrow[i] * (int)ks + vcol[i]); }
;     ...
;   f32x16 pA0, pA1, pB0, pB1; float mnA, mnB, alA, alB; bf16x8 pa0, pa1, pa2, pa3; const int NT = DIL ? 6 : seq / KVBLK;
;   DMA(0, 0); DMA(1, 1);
;   if constexpr (!DIL && MK_PP) { DMA(2, 2); asm volatile("s_waitcnt vmcnt(8)\n\ts_barrier" ::: "memory"); }
;   else asm volatile("s_waitcnt vmcnt(4)\n\ts_barrier" ::: "memory");
;     ...
;   if constexpr (DIL) {
;     const int rlo = wid >> 1;
;     for (int j = 0; j < NT; ++j) {
;       if (j + 2 < NT) DMA(j + 2, (j + 2) & 3);
	s_and_b32 s15, s23, 0x3fffffc0
	s_lshl_b32 s15, s15, 2
	v_mul_f32_e32 v2, v2, v3
	v_mul_f32_e32 v143, 0xbfb8aa3b, v2
	v_and_b32_e32 v2, 63, v10
	v_lshlrev_b32_e32 v3, 1, v10
	v_and_b32_e32 v7, 0xc0, v6
	v_lshlrev_b32_e32 v10, 8, v141
	v_and_b32_e32 v6, 0x70, v6
	v_or_b32_e32 v12, 32, v130
	s_add_i32 s15, s15, 0
	v_bitop3_b32 v146, v12, v10, v6 bitop3:0xde
	v_or_b32_e32 v12, 64, v130
	s_ashr_i32 s23, s23, 7
	s_add_i32 s15, s15, 0x20000
	v_bitop3_b32 v148, v12, v10, v6 bitop3:0xde
	v_or_b32_e32 v12, 0x60, v130
	s_add_i32 s25, s23, 2
	v_bitop3_b32 v145, v130, v10, v6 bitop3:0xde
	v_bitop3_b32 v149, v12, v10, v6 bitop3:0xde
	v_and_b32_e32 v6, 0x118, v13
	s_cmp_lg_u32 s88, -1
	v_lshl_add_u64 v[134:135], s[42:43], 0, v[0:1]
	v_lshl_add_u64 v[136:137], s[42:43], 0, v[8:9]
	v_and_or_b32 v0, v3, 32, v6
	s_cselect_b32 s42, s88, 0
	s_add_i32 s37, s37, s40
	v_mov_b32_e32 v14, v1
	v_mov_b32_e32 v15, v1
	v_cmp_gt_u32_e64 s[38:39], 32, v2
	v_add3_u32 v150, v7, s42, v0
	v_lshl_add_u64 v[138:139], s[0:1], 0, v[4:5]
	v_or_b32_e32 v152, s37, v11
	v_mov_b32_e32 v0, v1
	v_mov_b32_e32 v2, v1
	v_mov_b32_e32 v3, v1
	v_mov_b32_e32 v4, v1
	v_mov_b32_e32 v6, v1
	v_mov_b32_e32 v7, v1
	v_mov_b32_e32 v8, v1
	v_mov_b32_e32 v10, v1
	v_mov_b32_e32 v11, v1
	v_mov_b32_e32 v12, v1
	v_mov_b32_e32 v13, v1
	v_mov_b64_e32 v[64:65], v[14:15]
	v_mov_b64_e32 v[48:49], v[14:15]
	v_mov_b64_e32 v[32:33], v[14:15]
	v_mov_b64_e32 v[62:63], v[12:13]
	v_mov_b64_e32 v[60:61], v[10:11]
	v_mov_b64_e32 v[58:59], v[8:9]
	v_mov_b64_e32 v[56:57], v[6:7]
	v_mov_b64_e32 v[54:55], v[4:5]
	v_mov_b64_e32 v[52:53], v[2:3]
	v_mov_b64_e32 v[50:51], v[0:1]
	v_mov_b64_e32 v[46:47], v[12:13]
	v_mov_b64_e32 v[44:45], v[10:11]
	v_mov_b64_e32 v[42:43], v[8:9]
	v_mov_b64_e32 v[40:41], v[6:7]
	v_mov_b64_e32 v[38:39], v[4:5]
	v_mov_b64_e32 v[36:37], v[2:3]
	v_mov_b64_e32 v[34:35], v[0:1]
	v_mov_b64_e32 v[30:31], v[12:13]
	v_mov_b64_e32 v[28:29], v[10:11]
	v_mov_b64_e32 v[26:27], v[8:9]
	v_mov_b64_e32 v[24:25], v[6:7]
	v_mov_b64_e32 v[22:23], v[4:5]
	v_mov_b64_e32 v[20:21], v[2:3]
	v_mov_b64_e32 v[18:19], v[0:1]
	v_mov_b64_e32 v[16:17], v[14:15]
	s_cmp_gt_u32 s23, 1
	s_cselect_b32 s80, 1, 0
	s_sub_i32 s80, s23, s80
	s_lshl_b32 s21, s80, 14
	v_lshl_add_u32 v147, v141, 2, s15
	v_or_b32_e32 v151, s37, v131
	v_mov_b32_e32 v153, 0
	v_mov_b32_e32 v144, 0xf149f2ca
	s_lshl_b32 s37, s80, 6
	s_addk_i32 s37, 0xffc0
	v_mov_b64_e32 v[14:15], v[12:13]
	v_mov_b64_e32 v[12:13], v[10:11]
	v_mov_b64_e32 v[10:11], v[8:9]
	v_mov_b64_e32 v[8:9], v[6:7]
	v_mov_b64_e32 v[6:7], v[4:5]
	v_mov_b64_e32 v[4:5], v[2:3]
	v_mov_b64_e32 v[2:3], v[0:1]
	s_mov_b32 s46, s80
	s_movk_i32 s83, 0xffc0
	s_mov_b32 s84, 0
	v_add_u32_e32 v68, s83, v151
	v_add_u32_e32 v0, 0x80, v68
	v_max_i32_e32 v0, 0, v0
	v_min_i32_e32 v0, s12, v0
	s_add_i32 s0, s84, 0x8000
	v_lshlrev_b64 v[66:67], s10, v[0:1]
	v_add_u32_e32 v0, s83, v152
	s_and_b32 s0, s0, 0xc000
	v_add_u32_e32 v0, 0x80, v0
	s_add_i32 s1, s13, s0
	v_max_i32_e32 v0, 0, v0
	v_lshl_add_u64 v[66:67], v[66:67], 1, v[134:135]
	s_mov_b32 m0, s1
	v_min_i32_e32 v0, s12, v0
	global_load_lds_dwordx4 v[66:67], off
	v_lshlrev_b64 v[66:67], s10, v[0:1]
	v_add_u32_e32 v0, 0x84, v68
	v_max_i32_e32 v0, 0, v0
	s_add_i32 s0, s14, s0
	v_min_i32_e32 v0, s12, v0
	v_lshl_add_u64 v[66:67], v[66:67], 1, v[138:139]
	s_mov_b32 m0, s0
	v_lshlrev_b64 v[68:69], s10, v[0:1]
	global_load_lds_dwordx4 v[66:67], off
	v_lshl_add_u64 v[68:69], v[68:69], 1, v[136:137]
	s_add_i32 m0, s1, 0x400
	v_lshl_add_u64 v[66:67], v[66:67], 0, s[70:71]
	global_load_lds_dwordx4 v[68:69], off
	s_add_i32 m0, s0, 0x400
	s_nop 0
	global_load_lds_dwordx4 v[66:67], off
	s_mov_b32 s83, 0
	s_movk_i32 s84, 0x4000
	v_add_u32_e32 v68, s83, v151
	v_add_u32_e32 v0, 0x80, v68
	v_max_i32_e32 v0, 0, v0
	v_min_i32_e32 v0, s12, v0
	s_add_i32 s0, s84, 0x8000
	v_lshlrev_b64 v[66:67], s10, v[0:1]
	v_add_u32_e32 v0, s83, v152
	s_and_b32 s0, s0, 0xc000
	v_add_u32_e32 v0, 0x80, v0
	s_add_i32 s1, s13, s0
	v_max_i32_e32 v0, 0, v0
	v_lshl_add_u64 v[66:67], v[66:67], 1, v[134:135]
	s_mov_b32 m0, s1
	v_min_i32_e32 v0, s12, v0
	global_load_lds_dwordx4 v[66:67], off
	v_lshlrev_b64 v[66:67], s10, v[0:1]
	v_add_u32_e32 v0, 0x84, v68
	v_max_i32_e32 v0, 0, v0
	s_add_i32 s0, s14, s0
	v_min_i32_e32 v0, s12, v0
	v_lshl_add_u64 v[66:67], v[66:67], 1, v[138:139]
	s_mov_b32 m0, s0
	v_lshlrev_b64 v[68:69], s10, v[0:1]
	global_load_lds_dwordx4 v[66:67], off
	v_lshl_add_u64 v[68:69], v[68:69], 1, v[136:137]
	s_add_i32 m0, s1, 0x400
	v_lshl_add_u64 v[66:67], v[66:67], 0, s[70:71]
	global_load_lds_dwordx4 v[68:69], off
	s_add_i32 m0, s0, 0x400
	s_nop 0
	global_load_lds_dwordx4 v[66:67], off
	s_waitcnt vmcnt(8)
	s_barrier
	s_mov_b32 s82, 0
	s_branch .LBB0_140
